# on top of the 1.0327x stack: selected-loop late V-fragment reads hoisted (nops kept for trans hazard); RWKV wave 0 prefetches first three M rows of the forward substitution while idle in the P3 epoch
# baseline (speedup 1.0000x reference)
; #define MFMA32(a, b, c) __builtin_amdgcn_mfma_f32_32x32x16_bf16((a), (b), (c), 0, 0, 0)
; DI int crow16(int i, int hl) { return (i & 3) + 8 * (i >> 2) + 4 * hl; }
; __device__ __forceinline__ void rwkv_chunked(unsigned char* smem, CP p, int L, int b, int h) {
;     ...
;         if (wv == 1 || wv == 2) { const int vb = wv - 1;
;             acc = MFMA32(*(const bf16x8*)(UV + (32 * vb + qi) * 40 + 16 + 8 * hl), *(const bf16x8*)(MT1 + qi * 24 + 8 * hl), acc);
;             if (qi < 16) {
; #pragma unroll
;                 for (int i = 0; i < 16; ++i) Gs[(32 * vb + crow16(i, hl)) * 17 + qi] = acc[i]; }
;         }
;         __syncthreads();
;         if (wv == 0) {
;             float u[16], cur[16], nxt[16], gcur, gnxt = 0.f;
; #pragma unroll
;             for (int i = 0; i < 16; ++i) { cur[i] = 0.f; nxt[i] = 0.f; }
;             gcur = Gs[lane * 17];
; #pragma unroll
;             for (int t = 0; t < 16; ++t) {
;                 if (t + 1 < 16) { gnxt = Gs[lane * 17 + t + 1];
; #pragma unroll
;                     for (int i = 0; i <= t; ++i) nxt[i] = Mf[i * 17 + t + 1]; }
.LBB0_693:
	s_or_b64 exec, exec, vcc
	s_waitcnt lgkmcnt(0)
	s_barrier
	s_and_saveexec_b64 s[16:17], s[46:47]
	s_cbranch_execz .Lrw_mrows_skip
	v_mov_b32_e32 v0, 0xbe00
	ds_read2_b32 v[2:3], v0 offset0:1 offset1:2
	ds_read2_b32 v[4:5], v0 offset0:3 offset1:4
	ds_read2_b32 v[6:7], v0 offset0:5 offset1:6
	ds_read2_b32 v[8:9], v0 offset0:7 offset1:8
	ds_read2_b32 v[10:11], v0 offset0:9 offset1:10
	ds_read2_b32 v[12:13], v0 offset0:11 offset1:12
	ds_read2_b32 v[14:15], v0 offset0:13 offset1:14
	ds_read2_b32 v[130:131], v0 offset0:15 offset1:19
	ds_read2_b32 v[132:133], v0 offset0:20 offset1:21
	ds_read2_b32 v[134:135], v0 offset0:22 offset1:23
	ds_read2_b32 v[136:137], v0 offset0:24 offset1:25
	ds_read2_b32 v[138:139], v0 offset0:26 offset1:27
	ds_read2_b32 v[140:141], v0 offset0:28 offset1:29
	ds_read2_b32 v[142:143], v0 offset0:30 offset1:31
	ds_read2_b32 v[144:145], v0 offset0:32 offset1:37
	ds_read2_b32 v[146:147], v0 offset0:38 offset1:39
	ds_read2_b32 v[148:149], v0 offset0:40 offset1:41
	ds_read2_b32 v[150:151], v0 offset0:42 offset1:43
	ds_read2_b32 v[152:153], v0 offset0:44 offset1:45
	ds_read2_b32 v[156:157], v0 offset0:46 offset1:47
	ds_read2_b32 v[158:159], v0 offset0:48 offset1:49
.Lrw_mrows_skip:
	s_or_b64 exec, exec, s[16:17]
	s_and_saveexec_b64 s[16:17], s[50:51]
	s_cbranch_execz .LBB0_697
	ds_read_b128 v[2:5], v83 offset:18976
	ds_read_b128 v[6:9], v84 offset:24064
	s_waitcnt lgkmcnt(0)
	v_mfma_f32_32x32x16_bf16 v[32:47], v[2:5], v[6:9], v[32:47]
	s_and_saveexec_b64 vcc, s[10:11]
	s_cbranch_execz .LBB0_696
	v_add_u32_e32 v0, 0xcc00, v103
	s_nop 8
	ds_write2_b32 v0, v32, v33 offset0:160 offset1:177
	ds_write2_b32 v0, v34, v35 offset0:194 offset1:211
	v_add_u32_e32 v0, 0xd000, v103
	ds_write2_b32 v0, v36, v37 offset0:40 offset1:57
	ds_write2_b32 v0, v38, v39 offset0:74 offset1:91
	ds_write2_b32 v0, v40, v41 offset0:176 offset1:193
	ds_write2_b32 v0, v42, v43 offset0:210 offset1:227
	v_add_u32_e32 v0, 0xd400, v103
	ds_write2_b32 v0, v44, v45 offset0:56 offset1:73
	ds_write2_b32 v0, v46, v47 offset0:90 offset1:107

; DI bf16_t f2bf(float f) { return (bf16_t)(pack2(f, 0.f) & 0xFFFFu); }
; __device__ __forceinline__ void rwkv_chunked(unsigned char* smem, CP p, int L, int b, int h) {
;     ...
;         if (wv == 0) {
;             float u[16], cur[16], nxt[16], gcur, gnxt = 0.f;
; #pragma unroll
;             for (int i = 0; i < 16; ++i) { cur[i] = 0.f; nxt[i] = 0.f; }
;             gcur = Gs[lane * 17];
; #pragma unroll
;             for (int t = 0; t < 16; ++t) {
;                 if (t + 1 < 16) { gnxt = Gs[lane * 17 + t + 1];
; #pragma unroll
;                     for (int i = 0; i <= t; ++i) nxt[i] = Mf[i * 17 + t + 1]; }
;                 float x0 = gcur, x1 = 0.f;
; #pragma unroll
;                 for (int i = 0; i < t; ++i) { if (i & 1) x1 += u[i] * cur[i]; else x0 += u[i] * cur[i]; }
;                 u[t] = x0 + x1; UV[lane * 40 + t] = f2bf(u[t]);
; #pragma unroll
;                 for (int i = 0; i < 16; ++i) cur[i] = nxt[i];
;                 gcur = gnxt; }
;         }
.LBB0_697:
	s_or_b64 exec, exec, s[16:17]
	s_waitcnt lgkmcnt(0)
	s_barrier
	s_and_saveexec_b64 vcc, s[46:47]
	s_cbranch_execz .LBB0_699
	v_mov_b32_e32 v0, 0xbe00
	v_add_u32_e32 v154, 0xce80, v85
	ds_read2_b32 v[114:115], v154 offset0:0 offset1:1
	ds_read2_b32 v[116:117], v154 offset0:2 offset1:3
	ds_read2_b32 v[118:119], v154 offset0:4 offset1:5
	ds_read2_b32 v[120:121], v154 offset0:6 offset1:7
	ds_read2_b32 v[122:123], v154 offset0:8 offset1:9
	ds_read2_b32 v[124:125], v154 offset0:10 offset1:11
	ds_read2_b32 v[126:127], v154 offset0:12 offset1:13
	ds_read2_b32 v[128:129], v154 offset0:14 offset1:15
	s_waitcnt lgkmcnt(0)
	v_fmac_f32_e32 v115, v2, v114
	v_fmac_f32_e32 v116, v3, v114
	v_fmac_f32_e32 v117, v4, v114
	v_fmac_f32_e32 v118, v5, v114
	v_fmac_f32_e32 v119, v6, v114
	v_fmac_f32_e32 v120, v7, v114
	v_fmac_f32_e32 v121, v8, v114
	v_fmac_f32_e32 v122, v9, v114
	v_fmac_f32_e32 v123, v10, v114
	v_fmac_f32_e32 v124, v11, v114
	v_fmac_f32_e32 v125, v12, v114
	v_fmac_f32_e32 v126, v13, v114
	v_fmac_f32_e32 v127, v14, v114
	v_fmac_f32_e32 v128, v15, v114
	v_fmac_f32_e32 v129, v130, v114
	ds_read2_b32 v[160:161], v0 offset0:55 offset1:56
	ds_read2_b32 v[162:163], v0 offset0:57 offset1:58
	ds_read2_b32 v[164:165], v0 offset0:59 offset1:60
	ds_read2_b32 v[166:167], v0 offset0:61 offset1:62
	ds_read2_b32 v[168:169], v0 offset0:63 offset1:64
	ds_read2_b32 v[170:171], v0 offset0:65 offset1:66
	s_waitcnt lgkmcnt(12)
	v_fmac_f32_e32 v116, v131, v115
	v_fmac_f32_e32 v117, v132, v115
	v_fmac_f32_e32 v118, v133, v115
	v_fmac_f32_e32 v119, v134, v115
	v_fmac_f32_e32 v120, v135, v115
	v_fmac_f32_e32 v121, v136, v115
	v_fmac_f32_e32 v122, v137, v115
	v_fmac_f32_e32 v123, v138, v115
	v_fmac_f32_e32 v124, v139, v115
	v_fmac_f32_e32 v125, v140, v115
	v_fmac_f32_e32 v126, v141, v115
	v_fmac_f32_e32 v127, v142, v115
	v_fmac_f32_e32 v128, v143, v115
	v_fmac_f32_e32 v129, v144, v115
	ds_read2_b32 v[172:173], v0 offset0:73 offset1:74
	ds_read2_b32 v[174:175], v0 offset0:75 offset1:76
	ds_read2_b32 v[176:177], v0 offset0:77 offset1:78
	ds_read2_b32 v[178:179], v0 offset0:79 offset1:80
	ds_read2_b32 v[180:181], v0 offset0:81 offset1:82
	ds_read2_b32 v[182:183], v0 offset0:83 offset1:91
	s_waitcnt lgkmcnt(12)
	v_fmac_f32_e32 v117, v145, v116
	v_fmac_f32_e32 v118, v146, v116
	v_fmac_f32_e32 v119, v147, v116
	v_fmac_f32_e32 v120, v148, v116
	v_fmac_f32_e32 v121, v149, v116
	v_fmac_f32_e32 v122, v150, v116
	v_fmac_f32_e32 v123, v151, v116
	v_fmac_f32_e32 v124, v152, v116
	v_fmac_f32_e32 v125, v153, v116
	v_fmac_f32_e32 v126, v156, v116
	v_fmac_f32_e32 v127, v157, v116
	v_fmac_f32_e32 v128, v158, v116
	v_fmac_f32_e32 v129, v159, v116
	ds_read2_b32 v[184:185], v0 offset0:92 offset1:93
	ds_read2_b32 v[186:187], v0 offset0:94 offset1:95
	ds_read2_b32 v[188:189], v0 offset0:96 offset1:97
	ds_read2_b32 v[190:191], v0 offset0:98 offset1:99
	ds_read2_b32 v[192:193], v0 offset0:100 offset1:109
	s_waitcnt lgkmcnt(11)
	v_fmac_f32_e32 v118, v160, v117
	v_fmac_f32_e32 v119, v161, v117
	v_fmac_f32_e32 v120, v162, v117
	v_fmac_f32_e32 v121, v163, v117
	v_fmac_f32_e32 v122, v164, v117
	v_fmac_f32_e32 v123, v165, v117
	v_fmac_f32_e32 v124, v166, v117
	v_fmac_f32_e32 v125, v167, v117
	v_fmac_f32_e32 v126, v168, v117
	v_fmac_f32_e32 v127, v169, v117
	v_fmac_f32_e32 v128, v170, v117
	v_fmac_f32_e32 v129, v171, v117
	ds_read2_b32 v[2:3], v0 offset0:110 offset1:111
	ds_read2_b32 v[4:5], v0 offset0:112 offset1:113
	ds_read2_b32 v[6:7], v0 offset0:114 offset1:115
	ds_read2_b32 v[8:9], v0 offset0:116 offset1:117
	s_waitcnt lgkmcnt(9)
; DI bf16_t f2bf(float f) { return (bf16_t)(pack2(f, 0.f) & 0xFFFFu); }
; __device__ __forceinline__ void rwkv_chunked(unsigned char* smem, CP p, int L, int b, int h) {
;     ...
;         if (wv == 0) {
;             float u[16], cur[16], nxt[16], gcur, gnxt = 0.f;
; #pragma unroll
;             for (int i = 0; i < 16; ++i) { cur[i] = 0.f; nxt[i] = 0.f; }
;             gcur = Gs[lane * 17];
; #pragma unroll
;             for (int t = 0; t < 16; ++t) {
;                 if (t + 1 < 16) { gnxt = Gs[lane * 17 + t + 1];
; #pragma unroll
;                     for (int i = 0; i <= t; ++i) nxt[i] = Mf[i * 17 + t + 1]; }
;                 float x0 = gcur, x1 = 0.f;
; #pragma unroll
;                 for (int i = 0; i < t; ++i) { if (i & 1) x1 += u[i] * cur[i]; else x0 += u[i] * cur[i]; }
;                 u[t] = x0 + x1; UV[lane * 40 + t] = f2bf(u[t]);
; #pragma unroll
;                 for (int i = 0; i < 16; ++i) cur[i] = nxt[i];
;                 gcur = gnxt; }
;         }
	v_fmac_f32_e32 v119, v172, v118
	v_fmac_f32_e32 v120, v173, v118
	v_fmac_f32_e32 v121, v174, v118
	v_fmac_f32_e32 v122, v175, v118
	v_fmac_f32_e32 v123, v176, v118
	v_fmac_f32_e32 v124, v177, v118
	v_fmac_f32_e32 v125, v178, v118
	v_fmac_f32_e32 v126, v179, v118
	v_fmac_f32_e32 v127, v180, v118
	v_fmac_f32_e32 v128, v181, v118
	v_fmac_f32_e32 v129, v182, v118
	ds_read2_b32 v[10:11], v0 offset0:127 offset1:128
	ds_read2_b32 v[12:13], v0 offset0:129 offset1:130
	ds_read2_b32 v[14:15], v0 offset0:131 offset1:132
	ds_read2_b32 v[130:131], v0 offset0:133 offset1:134
	s_waitcnt lgkmcnt(8)
	v_fmac_f32_e32 v120, v183, v119
	v_fmac_f32_e32 v121, v184, v119
	v_fmac_f32_e32 v122, v185, v119
	v_fmac_f32_e32 v123, v186, v119
	v_fmac_f32_e32 v124, v187, v119
	v_fmac_f32_e32 v125, v188, v119
	v_fmac_f32_e32 v126, v189, v119
	v_fmac_f32_e32 v127, v190, v119
	v_fmac_f32_e32 v128, v191, v119
	v_fmac_f32_e32 v129, v192, v119
	ds_read2_b32 v[132:133], v0 offset0:145 offset1:146
	ds_read2_b32 v[134:135], v0 offset0:147 offset1:148
	ds_read2_b32 v[136:137], v0 offset0:149 offset1:150
	ds_read2_b32 v[138:139], v0 offset0:151 offset1:163
	s_waitcnt lgkmcnt(8)
	v_fmac_f32_e32 v121, v193, v120
	v_fmac_f32_e32 v122, v2, v120
	v_fmac_f32_e32 v123, v3, v120
	v_fmac_f32_e32 v124, v4, v120
	v_fmac_f32_e32 v125, v5, v120
	v_fmac_f32_e32 v126, v6, v120
	v_fmac_f32_e32 v127, v7, v120
	v_fmac_f32_e32 v128, v8, v120
	v_fmac_f32_e32 v129, v9, v120
	ds_read2_b32 v[140:141], v0 offset0:164 offset1:165
	ds_read2_b32 v[142:143], v0 offset0:166 offset1:167
	ds_read2_b32 v[144:145], v0 offset0:168 offset1:181
	s_waitcnt lgkmcnt(7)
	v_fmac_f32_e32 v122, v10, v121
	v_fmac_f32_e32 v123, v11, v121
	v_fmac_f32_e32 v124, v12, v121
	v_fmac_f32_e32 v125, v13, v121
	v_fmac_f32_e32 v126, v14, v121
	v_fmac_f32_e32 v127, v15, v121
	v_fmac_f32_e32 v128, v130, v121
	v_fmac_f32_e32 v129, v131, v121
	ds_read2_b32 v[146:147], v0 offset0:182 offset1:183
	ds_read2_b32 v[148:149], v0 offset0:184 offset1:185
	s_waitcnt lgkmcnt(5)
	v_fmac_f32_e32 v123, v132, v122
	v_fmac_f32_e32 v124, v133, v122
	v_fmac_f32_e32 v125, v134, v122
	v_fmac_f32_e32 v126, v135, v122
	v_fmac_f32_e32 v127, v136, v122
	v_fmac_f32_e32 v128, v137, v122
	v_fmac_f32_e32 v129, v138, v122
	ds_read2_b32 v[150:151], v0 offset0:199 offset1:200
	ds_read2_b32 v[152:153], v0 offset0:201 offset1:202
	s_waitcnt lgkmcnt(4)
	v_fmac_f32_e32 v124, v139, v123
	v_fmac_f32_e32 v125, v140, v123
	v_fmac_f32_e32 v126, v141, v123
	v_fmac_f32_e32 v127, v142, v123
	v_fmac_f32_e32 v128, v143, v123
	v_fmac_f32_e32 v129, v144, v123
	ds_read2_b32 v[156:157], v0 offset0:217 offset1:218
	ds_read2_b32 v[158:159], v0 offset0:219 offset1:235
	s_waitcnt lgkmcnt(4)
	v_fmac_f32_e32 v125, v145, v124
	v_fmac_f32_e32 v126, v146, v124
	v_fmac_f32_e32 v127, v147, v124
	v_fmac_f32_e32 v128, v148, v124
	v_fmac_f32_e32 v129, v149, v124
	ds_read2_b32 v[160:161], v0 offset0:236 offset1:253
	s_waitcnt lgkmcnt(3)
	v_fmac_f32_e32 v126, v150, v125
	v_fmac_f32_e32 v127, v151, v125
	v_fmac_f32_e32 v128, v152, v125
	v_fmac_f32_e32 v129, v153, v125
	s_waitcnt lgkmcnt(1)
	v_fmac_f32_e32 v127, v156, v126
	v_fmac_f32_e32 v128, v157, v126
	v_fmac_f32_e32 v129, v158, v126
	s_waitcnt lgkmcnt(0)
	v_fmac_f32_e32 v128, v159, v127
	v_fmac_f32_e32 v129, v160, v127
	s_waitcnt lgkmcnt(0)
	v_fmac_f32_e32 v129, v161, v128
	v_cvt_pk_bf16_f32 v2, v114, v115
	v_cvt_pk_bf16_f32 v3, v116, v117
	v_cvt_pk_bf16_f32 v4, v118, v119
	v_cvt_pk_bf16_f32 v5, v120, v121
	v_cvt_pk_bf16_f32 v6, v122, v123
	v_cvt_pk_bf16_f32 v7, v124, v125
	v_cvt_pk_bf16_f32 v8, v126, v127
	v_cvt_pk_bf16_f32 v9, v128, v129
	ds_write_b128 v86, v[2:5] offset:18944
	ds_write_b128 v86, v[6:9] offset:18960

; DI float shfl_xor_(float v, int mask, int lane) { return __int_as_float(__builtin_amdgcn_ds_bpermute((lane ^ mask) << 2, __float_as_int(v))); }
; #define MFMA32(a, b, c) __builtin_amdgcn_mfma_f32_32x32x16_bf16((a), (b), (c), 0, 0, 0)
; DI void flash_update(FlashState& st, f32x16& sc0, f32x16& sc1, const bf16_t* VT, int vs, int qi, int hl) {
;     ...
;     float mt = -INFINITY;
; #pragma unroll
;     for (int i = 0; i < 16; ++i) mt = fmaxf(mt, fmaxf(sc0[i], sc1[i]));
;     mt = fmaxf(mt, shfl_xor_(mt, 32, qi + 32 * hl));
;     const float mnew = fmaxf(st.m, mt), muse = (mnew == -INFINITY) ? 0.f : mnew;
;     const float alpha = __builtin_amdgcn_exp2f(st.m - muse);
;     float ls = 0.f;
; #pragma unroll
;     for (int i = 0; i < 16; ++i) { sc0[i] = __builtin_amdgcn_exp2f(sc0[i] - muse); sc1[i] = __builtin_amdgcn_exp2f(sc1[i] - muse); ls += sc0[i] + sc1[i]; }
;     st.l = st.l * alpha + ls; st.m = mnew;
;     st.o0 *= alpha; st.o1 *= alpha;
;     {
;         const bf16x8 p0 = pack8(sc0[0], sc0[1], sc0[2], sc0[3], sc0[4], sc0[5], sc0[6], sc0[7]);
;         const bf16x8 p1 = pack8(sc1[0], sc1[1], sc1[2], sc1[3], sc1[4], sc1[5], sc1[6], sc1[7]);
;         const bf16x8 wa0 = ld_vfrag(VT, qi * vs + 16 + 4 * hl), wb0 = ld_vfrag(VT, (32 + qi) * vs + 16 + 4 * hl);
;         const bf16x8 wa1 = ld_vfrag(VT, qi * vs + 48 + 4 * hl), wb1 = ld_vfrag(VT, (32 + qi) * vs + 48 + 4 * hl);
;         st.o0 = MFMA32(va0, p0, st.o0); st.o1 = MFMA32(vb0, p0, st.o1); st.o0 = MFMA32(va1, p1, st.o0); st.o1 = MFMA32(vb1, p1, st.o1);
;         const bf16x8 r0 = pack8(sc0[8], sc0[9], sc0[10], sc0[11], sc0[12], sc0[13], sc0[14], sc0[15]);
;         const bf16x8 r1 = pack8(sc1[8], sc1[9], sc1[10], sc1[11], sc1[12], sc1[13], sc1[14], sc1[15]);
;         st.o0 = MFMA32(wa0, r0, st.o0); st.o1 = MFMA32(wb0, r0, st.o1); st.o0 = MFMA32(wa1, r1, st.o0); st.o1 = MFMA32(wb1, r1, st.o1);
.LBB0_781:
	s_or_b64 exec, exec, s[10:11]
	v_max_f32_e32 v0, v34, v34
	s_nop 4
	v_max_f32_e32 v66, v50, v50
	v_max_f32_e32 v0, v66, v0
	v_max_f32_e32 v66, v35, v35
	v_max_f32_e32 v67, v51, v51
	v_max_f32_e32 v66, v67, v66
	s_mov_b32 s0, 0xff800000
	v_max3_f32 v0, v0, s0, v66
	v_max_f32_e32 v66, v36, v36
	v_max_f32_e32 v67, v52, v52
	v_max_f32_e32 v66, v67, v66
	v_max_f32_e32 v67, v37, v37
	v_max_f32_e32 v68, v53, v53
	v_max_f32_e32 v67, v68, v67
	v_max3_f32 v0, v0, v66, v67
	v_max_f32_e32 v66, v38, v38
	v_max_f32_e32 v67, v54, v54
	v_max_f32_e32 v66, v67, v66
	v_max_f32_e32 v67, v39, v39
	v_max_f32_e32 v68, v55, v55
	v_max_f32_e32 v67, v68, v67
	v_max3_f32 v0, v0, v66, v67
	v_max_f32_e32 v66, v40, v40
	v_max_f32_e32 v67, v56, v56
	v_max_f32_e32 v66, v67, v66
	v_max_f32_e32 v67, v41, v41
	v_max_f32_e32 v68, v57, v57
	v_max_f32_e32 v67, v68, v67
	v_max3_f32 v0, v0, v66, v67
	v_max_f32_e32 v66, v42, v42
	v_max_f32_e32 v67, v58, v58
	v_max_f32_e32 v66, v67, v66
	v_max_f32_e32 v67, v43, v43
	v_max_f32_e32 v68, v59, v59
	v_max_f32_e32 v67, v68, v67
	v_max3_f32 v0, v0, v66, v67
	v_max_f32_e32 v66, v44, v44
	v_max_f32_e32 v67, v60, v60
	v_max_f32_e32 v66, v67, v66
	v_max_f32_e32 v67, v45, v45
	v_max_f32_e32 v68, v61, v61
	v_max_f32_e32 v67, v68, v67
	v_max3_f32 v0, v0, v66, v67
	v_max_f32_e32 v66, v46, v46
	v_max_f32_e32 v67, v62, v62
	v_max_f32_e32 v66, v67, v66
	v_max_f32_e32 v67, v47, v47
	v_max_f32_e32 v68, v63, v63
	v_max_f32_e32 v67, v68, v67
	v_max3_f32 v0, v0, v66, v67
	v_max_f32_e32 v66, v48, v48
	v_max_f32_e32 v67, v64, v64
	v_max_f32_e32 v66, v67, v66
	v_max_f32_e32 v67, v49, v49
	v_max_f32_e32 v68, v65, v65
	v_max_f32_e32 v67, v68, v67
	v_max3_f32 v0, v0, v66, v67
	ds_bpermute_b32 v66, v149, v0
	v_add_u32_e32 v92, 0x2000, v147
	s_waitcnt lgkmcnt(0)
	v_max3_f32 v85, v152, v0, v66
	v_cmp_neq_f32_e32 vcc, s0, v85
	s_nop 1
	v_cndmask_b32_e32 v88, 0, v85, vcc
	v_sub_f32_e32 v0, v50, v88
	v_exp_f32_e32 v89, v0
	v_sub_f32_e32 v0, v34, v88
	v_exp_f32_e32 v90, v0
	v_sub_f32_e32 v0, v51, v88
	v_exp_f32_e32 v74, v0
	v_sub_f32_e32 v0, v35, v88
	v_exp_f32_e32 v0, v0
	v_add_f32_e32 v75, v89, v90
	v_sub_f32_e32 v38, v38, v88
	v_sub_f32_e32 v47, v47, v88
	v_pk_add_f32 v[34:35], v[74:75], v[0:1]
	s_nop 0
	v_pk_add_f32 v[50:51], v[34:35], v[34:35] op_sel_hi:[0,1]
	v_sub_f32_e32 v34, v52, v88
	v_exp_f32_e32 v75, v34
	v_sub_f32_e32 v34, v36, v88
	v_exp_f32_e32 v91, v34
	v_sub_f32_e32 v34, v53, v88
	v_exp_f32_e32 v76, v34
	v_sub_f32_e32 v34, v37, v88
	v_exp_f32_e32 v50, v34
	v_add_f32_e32 v77, v75, v91
	ds_read2_b64 v[34:37], v92 offset0:128 offset1:130
	v_pk_add_f32 v[52:53], v[76:77], v[50:51]
	v_sub_f32_e32 v51, v54, v88
	v_exp_f32_e32 v77, v38
	v_sub_f32_e32 v38, v55, v88
	v_pk_add_f32 v[52:53], v[52:53], v[52:53] op_sel_hi:[0,1]
	v_exp_f32_e32 v51, v51
	v_exp_f32_e32 v78, v38
	v_sub_f32_e32 v38, v39, v88
	v_exp_f32_e32 v52, v38
	v_add_u32_e32 v38, v146, v139
	v_add_f32_e32 v79, v51, v77
	v_add_u32_e32 v93, 0x3000, v38
	v_pk_add_f32 v[38:39], v[78:79], v[52:53]
	s_nop 0
	v_pk_add_f32 v[80:81], v[38:39], v[38:39] op_sel_hi:[0,1]
	v_sub_f32_e32 v38, v56, v88
	v_exp_f32_e32 v53, v38
	v_sub_f32_e32 v38, v40, v88
	v_exp_f32_e32 v79, v38
	v_sub_f32_e32 v38, v57, v88
	v_exp_f32_e32 v82, v38
	v_sub_f32_e32 v38, v41, v88
	v_exp_f32_e32 v80, v38
	v_add_f32_e32 v83, v53, v79
	ds_read2_b64 v[54:57], v93 offset0:192 offset1:194
	ds_read2_b64 v[66:69], v92 offset0:136 offset1:138
	ds_read2_b64 v[70:73], v93 offset0:200 offset1:202
	ds_read2_b64 v[180:183], v92 offset0:132 offset1:134
	ds_read2_b64 v[184:187], v93 offset0:196 offset1:198
	ds_read2_b64 v[188:191], v92 offset0:140 offset1:142
	ds_read2_b64 v[216:219], v93 offset0:204 offset1:206
	v_pk_add_f32 v[38:39], v[82:83], v[80:81]
	s_nop 0
	v_pk_add_f32 v[38:39], v[38:39], v[38:39] op_sel_hi:[0,1]
	v_sub_f32_e32 v38, v58, v88
	v_exp_f32_e32 v81, v38
	v_sub_f32_e32 v38, v42, v88
	v_exp_f32_e32 v83, v38
	v_sub_f32_e32 v38, v59, v88
	v_exp_f32_e32 v58, v38
	v_sub_f32_e32 v38, v43, v88
	v_exp_f32_e32 v38, v38
	v_add_f32_e32 v59, v81, v83
	v_sub_f32_e32 v42, v152, v88
	v_exp_f32_e32 v84, v42
	v_pk_add_f32 v[40:41], v[58:59], v[38:39]
	v_sub_f32_e32 v39, v60, v88
	v_pk_add_f32 v[40:41], v[40:41], v[40:41] op_sel_hi:[0,1]
	v_sub_f32_e32 v40, v44, v88
	v_exp_f32_e32 v59, v40
	v_sub_f32_e32 v40, v61, v88
	v_exp_f32_e32 v39, v39
	v_exp_f32_e32 v60, v40
	v_sub_f32_e32 v40, v45, v88
	v_exp_f32_e32 v40, v40
	v_add_f32_e32 v61, v39, v59
	v_pk_mul_f32 v[32:33], v[32:33], v[84:85] op_sel_hi:[1,0]
	v_pk_mul_f32 v[30:31], v[30:31], v[84:85] op_sel_hi:[1,0]
	v_pk_add_f32 v[42:43], v[60:61], v[40:41]
	v_pk_mul_f32 v[28:29], v[28:29], v[84:85] op_sel_hi:[1,0]
	v_pk_add_f32 v[86:87], v[42:43], v[42:43] op_sel_hi:[0,1]
	v_pk_mul_f32 v[26:27], v[26:27], v[84:85] op_sel_hi:[1,0]
	v_pk_mul_f32 v[24:25], v[24:25], v[84:85] op_sel_hi:[1,0]
	v_pk_mul_f32 v[22:23], v[22:23], v[84:85] op_sel_hi:[1,0]
	v_pk_mul_f32 v[20:21], v[20:21], v[84:85] op_sel_hi:[1,0]
	v_pk_mul_f32 v[18:19], v[18:19], v[84:85] op_sel_hi:[1,0]
	v_pk_mul_f32 v[16:17], v[16:17], v[84:85] op_sel_hi:[1,0]
	v_cvt_pk_bf16_f32 v42, v89, v74
	v_cvt_pk_bf16_f32 v43, v75, v76
	v_cvt_pk_bf16_f32 v44, v51, v78
	v_cvt_pk_bf16_f32 v45, v53, v82
	v_pk_mul_f32 v[14:15], v[14:15], v[84:85] op_sel_hi:[1,0]
	v_pk_mul_f32 v[12:13], v[12:13], v[84:85] op_sel_hi:[1,0]
	v_pk_mul_f32 v[10:11], v[10:11], v[84:85] op_sel_hi:[1,0]
	v_pk_mul_f32 v[8:9], v[8:9], v[84:85] op_sel_hi:[1,0]
	v_pk_mul_f32 v[6:7], v[6:7], v[84:85] op_sel_hi:[1,0]
	v_pk_mul_f32 v[4:5], v[4:5], v[84:85] op_sel_hi:[1,0]
	v_pk_mul_f32 v[2:3], v[2:3], v[84:85] op_sel_hi:[1,0]
	s_waitcnt lgkmcnt(7)
; #define MFMA32(a, b, c) __builtin_amdgcn_mfma_f32_32x32x16_bf16((a), (b), (c), 0, 0, 0)
; DI void flash_update(FlashState& st, f32x16& sc0, f32x16& sc1, const bf16_t* VT, int vs, int qi, int hl) {
;     ...
;         const bf16x8 p0 = pack8(sc0[0], sc0[1], sc0[2], sc0[3], sc0[4], sc0[5], sc0[6], sc0[7]);
;         const bf16x8 p1 = pack8(sc1[0], sc1[1], sc1[2], sc1[3], sc1[4], sc1[5], sc1[6], sc1[7]);
;         const bf16x8 wa0 = ld_vfrag(VT, qi * vs + 16 + 4 * hl), wb0 = ld_vfrag(VT, (32 + qi) * vs + 16 + 4 * hl);
;         const bf16x8 wa1 = ld_vfrag(VT, qi * vs + 48 + 4 * hl), wb1 = ld_vfrag(VT, (32 + qi) * vs + 48 + 4 * hl);
;         st.o0 = MFMA32(va0, p0, st.o0); st.o1 = MFMA32(vb0, p0, st.o1); st.o0 = MFMA32(va1, p1, st.o0); st.o1 = MFMA32(vb1, p1, st.o1);
;         const bf16x8 r0 = pack8(sc0[8], sc0[9], sc0[10], sc0[11], sc0[12], sc0[13], sc0[14], sc0[15]);
;         const bf16x8 r1 = pack8(sc1[8], sc1[9], sc1[10], sc1[11], sc1[12], sc1[13], sc1[14], sc1[15]);
;         st.o0 = MFMA32(wa0, r0, st.o0); st.o1 = MFMA32(wb0, r0, st.o1); st.o0 = MFMA32(wa1, r1, st.o0); st.o1 = MFMA32(wb1, r1, st.o1);
	v_mfma_f32_32x32x16_bf16 v[18:33], v[34:37], v[42:45], v[18:33]
	v_sub_f32_e32 v34, v62, v88
	v_exp_f32_e32 v41, v34
	v_cvt_pk_bf16_f32 v34, v90, v0
	v_cvt_pk_bf16_f32 v35, v91, v50
	v_cvt_pk_bf16_f32 v36, v77, v52
	v_cvt_pk_bf16_f32 v37, v79, v80
	v_exp_f32_e32 v86, v47
	s_waitcnt lgkmcnt(6)
	v_mfma_f32_32x32x16_bf16 v[2:17], v[54:57], v[42:45], v[2:17]
	v_sub_f32_e32 v42, v46, v88
	v_exp_f32_e32 v0, v42
	v_sub_f32_e32 v42, v63, v88
	v_exp_f32_e32 v46, v42
	v_sub_f32_e32 v42, v64, v88
	v_exp_f32_e32 v55, v42
	s_nop 0
	s_waitcnt lgkmcnt(5)
	v_mfma_f32_32x32x16_bf16 v[18:33], v[66:69], v[34:37], v[18:33]
	v_cvt_pk_bf16_f32 v50, v81, v58
	v_cvt_pk_bf16_f32 v51, v39, v60
	v_cvt_pk_bf16_f32 v52, v41, v46
	v_add_f32_e32 v47, v41, v0
	v_sub_f32_e32 v39, v48, v88
	v_exp_f32_e32 v48, v39
	v_mov_b32_e32 v152, v85
	s_waitcnt lgkmcnt(4)
	v_mfma_f32_32x32x16_bf16 v[2:17], v[70:73], v[34:37], v[2:17]
	v_sub_f32_e32 v34, v65, v88
	v_exp_f32_e32 v54, v34
	s_nop 0
	v_cvt_pk_bf16_f32 v53, v55, v54
	v_add_f32_e32 v55, v55, v48
	s_waitcnt lgkmcnt(3)
	v_mfma_f32_32x32x16_bf16 v[18:33], v[180:183], v[50:53], v[18:33]
	v_add_f32_e64 v42, v46, v86
	v_add_f32_e64 v43, v47, v87
	v_add_f32_e64 v46, v42, v42
	v_add_f32_e64 v47, v42, v43
	s_nop 0
	s_waitcnt lgkmcnt(2)
	v_mfma_f32_32x32x16_bf16 v[2:17], v[184:187], v[50:53], v[2:17]
	v_sub_f32_e32 v34, v49, v88
	v_exp_f32_e32 v46, v34
	v_cvt_pk_bf16_f32 v34, v83, v38
	v_cvt_pk_bf16_f32 v35, v59, v40
	s_nop 0
	v_cvt_pk_bf16_f32 v36, v0, v86
	v_cvt_pk_bf16_f32 v37, v48, v46
	s_waitcnt lgkmcnt(1)
	s_nop 0
	v_mfma_f32_32x32x16_bf16 v[18:33], v[188:191], v[34:37], v[18:33]
	v_add_f32_e64 v42, v54, v46
	v_add_f32_e64 v43, v55, v47
	v_add_f32_e32 v0, v42, v43
	v_fmac_f32_e32 v0, v140, v84
	v_mov_b32_e32 v140, v0
	s_waitcnt lgkmcnt(0)
	v_mfma_f32_32x32x16_bf16 v[2:17], v[216:219], v[34:37], v[2:17]
